# P4-L0 context attention tasks moved to workgroups 64-127 and 160-223 to balance the phase critical path
# baseline (speedup 1.0000x reference)
.LBB0_328:
	s_sub_i32 s0, s35, 0x200
	s_sub_i32 s1, s35, 0x500
	s_cmp_lt_u32 s1, 0x200
	s_cselect_b32 s13, 1, 0
	s_add_i32 s1, s1, 0x200
	s_cmp_lt_u32 s0, 0x200
	s_cselect_b32 s0, s0, 0x7fff
	s_cmp_eq_u32 s13, 1
	s_cselect_b32 s35, s1, s0
	s_cmpk_gt_i32 s35, 0x3ff
	v_readlane_b32 s2, v250, 23
	s_cselect_b64 s[0:1], -1, 0
	v_readlane_b32 s3, v250, 24
	s_or_b64 s[0:1], s[2:3], s[0:1]
	v_readlane_b32 s14, v252, 51
	s_and_b64 vcc, exec, s[0:1]
	v_readlane_b32 s2, v252, 28
	v_readlane_b32 s3, v252, 29
	v_readlane_b32 s15, v252, 52
	s_mov_b32 s13, 0x20000
	s_cbranch_vccnz .LBB0_331
	v_readlane_b32 s0, v252, 55
	v_mov_b32_e32 v173, v195
	v_readlane_b32 s1, v252, 56
	v_cmp_lt_i32_e32 vcc, v236, v234
	v_readlane_b32 s52, v252, 12
	v_lshl_add_u64 v[148:149], s[0:1], 0, v[172:173]
	s_lshl_b32 s0, s12, 3
	v_readlane_b32 s1, v251, 56
	v_cndmask_b32_e32 v2, v233, v236, vcc
	v_cmp_lt_i32_e32 vcc, v235, v234
	s_lshl_b32 s4, s35, 3
	s_lshl_b32 s0, s12, 4
	v_readlane_b32 s1, v251, 63
	v_lshlrev_b32_e32 v176, 2, v2
	v_cndmask_b32_e32 v2, v233, v235, vcc
	v_mov_b32_e32 v175, v195
	v_readlane_b32 s60, v252, 20
	v_readlane_b32 s61, v252, 21
	s_lshl_b32 s5, s35, 4
	s_lshl_b32 s0, s12, 1
	v_readlane_b32 s1, v250, 0
	v_lshlrev_b32_e32 v177, 2, v2
	s_mov_b64 s[22:23], 0x3000
	s_mov_b64 s[20:21], 0x2000
	v_lshl_add_u64 v[146:147], s[60:61], 0, v[174:175]
	s_lshl_b32 s6, s35, 1
	v_lshlrev_b32_e32 v194, 1, v170
	v_readlane_b32 s9, v250, 17
	v_readlane_b32 s12, v250, 1
	s_mov_b32 s17, 0x240000
	v_readlane_b32 s53, v252, 13
	v_readlane_b32 s54, v252, 14
	v_readlane_b32 s55, v252, 15
	v_readlane_b32 s56, v252, 16
	v_readlane_b32 s57, v252, 17
	v_readlane_b32 s58, v252, 18
	v_readlane_b32 s59, v252, 19
	v_readlane_b32 s62, v252, 22
	v_readlane_b32 s63, v252, 23
	v_readlane_b32 s64, v252, 24
	v_readlane_b32 s65, v252, 25
	v_readlane_b32 s66, v252, 26
	v_readlane_b32 s67, v252, 27
